# idx pass 1/2: score + remainder-K prefetch issued before the preceding histogram scan (latency hidden behind the scan)
# baseline (speedup 1.0000x reference)
; DI void idx_scan(const u32* hq, int need, u32* outbin, u32* outneed, int q, int lane) {
;   u32 c = 0;
; #pragma unroll
;   for (int w = 0; w < 8; ++w) { u32 v = hq[8 * lane + w]; c += (v & 0xffffu) + (v >> 16); }
;   u32 incl = c;
; #pragma unroll
;   for (int o = 1; o < 64; o <<= 1) { u32 v = __shfl_down(incl, o); if (lane + o < 64) incl += v; }
;   const u32 above = incl - c;
;   if ((int)above < need && need <= (int)incl) {
; template <int PASS>
; DI void idx_pass(const u16* kp, const bf16x8 (&qf)[8], const float (&wq)[8], int wave, int ntile, int lm, int lg, int tq, bool selall,
;                  u32 bA, u32 pfx, u32* hist, u32* maskw, u32* cand, u32* ccnt) {
;   auto ldk = [&](int t) { return *(const bf16x8*)(kp + (size_t)(t < ntile ? t : 0) * 512); };
;   int kt = wave;
;   bf16x8 ka = ldk(kt), kb = ldk(kt + 4);
.LBB0_409:
	s_or_b64 exec, exec, s[2:3]
	s_waitcnt vmcnt(1)
	v_and_b32_e32 v43, 63, v207
	v_cmp_ne_u32_e64 s[4:5], 63, v43
	v_lshl_add_u32 v140, v109, 13, v96
	v_lshl_add_u32 v139, v141, 5, v140
	v_addc_co_u32_e64 v44, s[4:5], 0, v207, s[4:5]
	s_waitcnt lgkmcnt(0)
	s_barrier
	s_waitcnt vmcnt(0)
	s_cbranch_vccz .Lidx1_ne
	v_sub_u32_e32 v160, v97, v109
	v_subrev_u32_e32 v160, 5, v160
	v_and_b32_e32 v160, -8, v160
	v_add_u32_e32 v160, v160, v109
	v_add_u32_e32 v162, 12, v160
	v_add_u32_e32 v160, 8, v160
	v_cmp_le_i32_e64 s[4:5], v160, v97
	v_cmp_le_i32_e64 s[8:9], v162, v97
	v_mov_b32_e32 v161, 0
	v_mov_b32_e32 v163, 0
	v_cndmask_b32_e64 v160, 0, v160, s[4:5]
	v_cndmask_b32_e64 v162, 0, v162, s[8:9]
	v_lshlrev_b64 v[160:161], 10, v[160:161]
	v_lshlrev_b64 v[162:163], 10, v[162:163]
	v_lshl_add_u64 v[160:161], v[90:91], 0, v[160:161]
	v_lshl_add_u64 v[162:163], v[90:91], 0, v[162:163]
	global_load_dwordx4 v[126:129], v[160:161], off
	global_load_dwordx4 v[130:133], v[162:163], off
	v_lshl_add_u32 v134, v109, 10, v250
	s_add_u32 s92, s90, 0x1000
	s_addc_u32 s93, s91, 0
	v_readfirstlane_b32 s88, v109
	v_readfirstlane_b32 s89, v97
	global_load_dwordx4 v[110:113], v134, s[90:91]
	global_load_dwordx4 v[114:117], v134, s[92:93]
	v_add_u32_e32 v135, 0x2000, v134
	global_load_dwordx4 v[118:121], v135, s[90:91]
	global_load_dwordx4 v[122:125], v135, s[92:93]
	v_add_u32_e32 v134, 0x4000, v134
.Lidx1_ne:
	v_lshl_add_u32 v46, v109, 13, v96
	v_and_b32_e32 v48, 63, v207
	v_lshl_add_u32 v47, v109, 4, v96
	v_lshl_add_u32 v46, v48, 5, v46
	v_add_u32_e32 v47, 0xc000, v47
	ds_read_b128 v[168:171], v46
	ds_read_b128 v[172:175], v46 offset:16
	ds_read_b128 v[176:179], v46 offset:2048
	ds_read_b128 v[180:183], v46 offset:2064
	ds_read_b128 v[184:187], v46 offset:4096
	ds_read_b128 v[188:191], v46 offset:4112
	ds_read_b128 v[226:229], v46 offset:6144
	ds_read_b128 v[230:233], v46 offset:6160
	v_mov_b32_e32 v238, 0x100
	v_mov_b32_e32 v239, 0x100
	v_mov_b32_e32 v240, 0x100
	v_mov_b32_e32 v241, 0x100
	s_waitcnt lgkmcnt(0)
	v_add3_u32 v192, v168, v169, v170
	v_add3_u32 v193, v176, v177, v178
	v_add3_u32 v194, v184, v185, v186
	v_add3_u32 v195, v226, v227, v228
	v_add3_u32 v192, v192, v171, v172
	v_add3_u32 v193, v193, v179, v180
	v_add3_u32 v194, v194, v187, v188
	v_add3_u32 v195, v195, v229, v230
	v_add3_u32 v192, v192, v173, v174
	v_add3_u32 v193, v193, v181, v182
	v_add3_u32 v194, v194, v189, v190
	v_add3_u32 v195, v195, v231, v232
	v_add_u32_e32 v192, v192, v175
	v_add_u32_e32 v193, v193, v183
	v_add_u32_e32 v194, v194, v191
	v_add_u32_e32 v195, v195, v233
	v_add_u32_sdwa v192, v192, v192 dst_sel:DWORD dst_unused:UNUSED_PAD src0_sel:WORD_0 src1_sel:WORD_1
	v_add_u32_sdwa v193, v193, v193 dst_sel:DWORD dst_unused:UNUSED_PAD src0_sel:WORD_0 src1_sel:WORD_1
	v_add_u32_sdwa v194, v194, v194 dst_sel:DWORD dst_unused:UNUSED_PAD src0_sel:WORD_0 src1_sel:WORD_1
	v_add_u32_sdwa v195, v195, v195 dst_sel:DWORD dst_unused:UNUSED_PAD src0_sel:WORD_0 src1_sel:WORD_1
	v_mov_b32_e32 v234, v192
	v_mov_b32_e32 v235, v193
	v_mov_b32_e32 v236, v194
	v_mov_b32_e32 v237, v195
	v_add_u32_dpp v234, v234, v234 row_shl:1 row_mask:0xf bank_mask:0xf
	v_add_u32_dpp v235, v235, v235 row_shl:1 row_mask:0xf bank_mask:0xf
	v_add_u32_dpp v236, v236, v236 row_shl:1 row_mask:0xf bank_mask:0xf
	v_add_u32_dpp v237, v237, v237 row_shl:1 row_mask:0xf bank_mask:0xf
	v_add_u32_dpp v234, v234, v234 row_shl:2 row_mask:0xf bank_mask:0xf
	v_add_u32_dpp v235, v235, v235 row_shl:2 row_mask:0xf bank_mask:0xf
	v_add_u32_dpp v236, v236, v236 row_shl:2 row_mask:0xf bank_mask:0xf
	v_add_u32_dpp v237, v237, v237 row_shl:2 row_mask:0xf bank_mask:0xf
	v_add_u32_dpp v234, v234, v234 row_shl:4 row_mask:0xf bank_mask:0xf
	v_add_u32_dpp v235, v235, v235 row_shl:4 row_mask:0xf bank_mask:0xf
	v_add_u32_dpp v236, v236, v236 row_shl:4 row_mask:0xf bank_mask:0xf
	v_add_u32_dpp v237, v237, v237 row_shl:4 row_mask:0xf bank_mask:0xf
	v_add_u32_dpp v234, v234, v234 row_shl:8 row_mask:0xf bank_mask:0xf
	v_add_u32_dpp v235, v235, v235 row_shl:8 row_mask:0xf bank_mask:0xf
	v_add_u32_dpp v236, v236, v236 row_shl:8 row_mask:0xf bank_mask:0xf
	v_add_u32_dpp v237, v237, v237 row_shl:8 row_mask:0xf bank_mask:0xf
	s_nop 1
	v_readlane_b32 s40, v234, 16
	v_readlane_b32 s41, v234, 32
	v_readlane_b32 s42, v234, 48
	v_readlane_b32 s43, v235, 16
	v_readlane_b32 s44, v235, 32
	v_readlane_b32 s45, v235, 48
	v_readlane_b32 s46, v236, 16
	v_readlane_b32 s47, v236, 32
	v_readlane_b32 s48, v236, 48
	v_readlane_b32 s49, v237, 16
	v_readlane_b32 s50, v237, 32
	v_readlane_b32 s51, v237, 48
	s_nop 0
	s_add_i32 s41, s41, s42
	s_add_i32 s40, s40, s41
	s_add_i32 s44, s44, s45
	s_add_i32 s43, s43, s44
	s_add_i32 s47, s47, s48
	s_add_i32 s46, s46, s47
	s_add_i32 s50, s50, s51
	s_add_i32 s49, s49, s50
	s_mov_b32 exec_lo, 0xffff
	s_mov_b32 exec_hi, 0
	v_add_u32_e32 v234, s40, v234
	v_add_u32_e32 v235, s43, v235
	v_add_u32_e32 v236, s46, v236
	v_add_u32_e32 v237, s49, v237
	s_mov_b32 exec_lo, 0xffff0000
	v_add_u32_e32 v234, s41, v234
	v_add_u32_e32 v235, s44, v235
	v_add_u32_e32 v236, s47, v236
	v_add_u32_e32 v237, s50, v237
	s_mov_b32 exec_lo, 0
	s_mov_b32 exec_hi, 0xffff
	v_add_u32_e32 v234, s42, v234
	v_add_u32_e32 v235, s45, v235
	v_add_u32_e32 v236, s48, v236
	v_add_u32_e32 v237, s51, v237
	s_mov_b64 exec, -1
	v_sub_u32_e32 v158, v234, v192
	v_sub_u32_e32 v159, v235, v193
	v_sub_u32_e32 v160, v236, v194
	v_sub_u32_e32 v161, v237, v195
	v_cmp_lt_u32_e64 s[4:5], v158, v238
	v_cmp_lt_u32_e64 s[6:7], v159, v239
	v_cmp_lt_u32_e64 s[8:9], v160, v240
	v_cmp_lt_u32_e64 s[28:29], v161, v241
	v_cmp_le_u32_e64 s[40:41], v238, v234
	v_cmp_le_u32_e64 s[42:43], v239, v235
; DI void idx_scan(const u32* hq, int need, u32* outbin, u32* outneed, int q, int lane) {
;     ...
;   if ((int)above < need && need <= (int)incl) {
;     u32 cum = above;
;     ...
;       u32 cnt = (hq[bin >> 1] >> ((bin & 1) * 16)) & 0xffffu;
;       if ((int)(cum + cnt) >= need) { outbin[q] = (u32)bin; outneed[q] = (u32)need - cum; break; }
;       cum += cnt;
;     }
	v_cmp_le_u32_e64 s[44:45], v240, v236
	v_cmp_le_u32_e64 s[46:47], v241, v237
	v_mov_b32_e32 v42, v158
	v_mov_b32_e32 v43, v159
	v_mov_b32_e32 v44, v160
	v_mov_b32_e32 v45, v161
	v_mov_b32_e32 v162, 15
	v_mov_b32_e32 v163, 15
	v_mov_b32_e32 v164, 15
	v_mov_b32_e32 v165, 15
	s_and_b64 s[40:41], s[40:41], s[4:5]
	s_and_b64 s[42:43], s[42:43], s[6:7]
	s_and_b64 s[44:45], s[44:45], s[8:9]
	s_and_b64 s[46:47], s[46:47], s[28:29]
	v_add_u32_sdwa v158, v175, v158 dst_sel:DWORD dst_unused:UNUSED_PAD src0_sel:WORD_1 src1_sel:DWORD
	v_add_u32_sdwa v159, v183, v159 dst_sel:DWORD dst_unused:UNUSED_PAD src0_sel:WORD_1 src1_sel:DWORD
	v_add_u32_sdwa v160, v191, v160 dst_sel:DWORD dst_unused:UNUSED_PAD src0_sel:WORD_1 src1_sel:DWORD
	v_add_u32_sdwa v161, v233, v161 dst_sel:DWORD dst_unused:UNUSED_PAD src0_sel:WORD_1 src1_sel:DWORD
	v_cmp_lt_u32_e64 s[4:5], v158, v238
	v_cmp_lt_u32_e64 s[6:7], v159, v239
	v_cmp_lt_u32_e64 s[8:9], v160, v240
	v_cmp_lt_u32_e64 s[28:29], v161, v241
	v_cndmask_b32_e64 v42, v42, v158, s[4:5]
	v_cndmask_b32_e64 v162, v162, 14, s[4:5]
	v_cndmask_b32_e64 v43, v43, v159, s[6:7]
	v_cndmask_b32_e64 v163, v163, 14, s[6:7]
	v_cndmask_b32_e64 v44, v44, v160, s[8:9]
	v_cndmask_b32_e64 v164, v164, 14, s[8:9]
	v_cndmask_b32_e64 v45, v45, v161, s[28:29]
	v_cndmask_b32_e64 v165, v165, 14, s[28:29]
	v_add_u32_sdwa v158, v175, v158 dst_sel:DWORD dst_unused:UNUSED_PAD src0_sel:WORD_0 src1_sel:DWORD
	v_add_u32_sdwa v159, v183, v159 dst_sel:DWORD dst_unused:UNUSED_PAD src0_sel:WORD_0 src1_sel:DWORD
	v_add_u32_sdwa v160, v191, v160 dst_sel:DWORD dst_unused:UNUSED_PAD src0_sel:WORD_0 src1_sel:DWORD
	v_add_u32_sdwa v161, v233, v161 dst_sel:DWORD dst_unused:UNUSED_PAD src0_sel:WORD_0 src1_sel:DWORD
	v_cmp_lt_u32_e64 s[4:5], v158, v238
	v_cmp_lt_u32_e64 s[6:7], v159, v239
	v_cmp_lt_u32_e64 s[8:9], v160, v240
	v_cmp_lt_u32_e64 s[28:29], v161, v241
	v_cndmask_b32_e64 v42, v42, v158, s[4:5]
	v_cndmask_b32_e64 v162, v162, 13, s[4:5]
	v_cndmask_b32_e64 v43, v43, v159, s[6:7]
	v_cndmask_b32_e64 v163, v163, 13, s[6:7]
	v_cndmask_b32_e64 v44, v44, v160, s[8:9]
	v_cndmask_b32_e64 v164, v164, 13, s[8:9]
	v_cndmask_b32_e64 v45, v45, v161, s[28:29]
	v_cndmask_b32_e64 v165, v165, 13, s[28:29]
	v_add_u32_sdwa v158, v174, v158 dst_sel:DWORD dst_unused:UNUSED_PAD src0_sel:WORD_1 src1_sel:DWORD
	v_add_u32_sdwa v159, v182, v159 dst_sel:DWORD dst_unused:UNUSED_PAD src0_sel:WORD_1 src1_sel:DWORD
	v_add_u32_sdwa v160, v190, v160 dst_sel:DWORD dst_unused:UNUSED_PAD src0_sel:WORD_1 src1_sel:DWORD
	v_add_u32_sdwa v161, v232, v161 dst_sel:DWORD dst_unused:UNUSED_PAD src0_sel:WORD_1 src1_sel:DWORD
	v_cmp_lt_u32_e64 s[4:5], v158, v238
	v_cmp_lt_u32_e64 s[6:7], v159, v239
	v_cmp_lt_u32_e64 s[8:9], v160, v240
	v_cmp_lt_u32_e64 s[28:29], v161, v241
	v_cndmask_b32_e64 v42, v42, v158, s[4:5]
	v_cndmask_b32_e64 v162, v162, 12, s[4:5]
	v_cndmask_b32_e64 v43, v43, v159, s[6:7]
	v_cndmask_b32_e64 v163, v163, 12, s[6:7]
	v_cndmask_b32_e64 v44, v44, v160, s[8:9]
	v_cndmask_b32_e64 v164, v164, 12, s[8:9]
	v_cndmask_b32_e64 v45, v45, v161, s[28:29]
	v_cndmask_b32_e64 v165, v165, 12, s[28:29]
	v_add_u32_sdwa v158, v174, v158 dst_sel:DWORD dst_unused:UNUSED_PAD src0_sel:WORD_0 src1_sel:DWORD
	v_add_u32_sdwa v159, v182, v159 dst_sel:DWORD dst_unused:UNUSED_PAD src0_sel:WORD_0 src1_sel:DWORD
	v_add_u32_sdwa v160, v190, v160 dst_sel:DWORD dst_unused:UNUSED_PAD src0_sel:WORD_0 src1_sel:DWORD
	v_add_u32_sdwa v161, v232, v161 dst_sel:DWORD dst_unused:UNUSED_PAD src0_sel:WORD_0 src1_sel:DWORD
	v_cmp_lt_u32_e64 s[4:5], v158, v238
	v_cmp_lt_u32_e64 s[6:7], v159, v239
	v_cmp_lt_u32_e64 s[8:9], v160, v240
	v_cmp_lt_u32_e64 s[28:29], v161, v241
	v_cndmask_b32_e64 v42, v42, v158, s[4:5]
	v_cndmask_b32_e64 v162, v162, 11, s[4:5]
	v_cndmask_b32_e64 v43, v43, v159, s[6:7]
	v_cndmask_b32_e64 v163, v163, 11, s[6:7]
	v_cndmask_b32_e64 v44, v44, v160, s[8:9]
	v_cndmask_b32_e64 v164, v164, 11, s[8:9]
	v_cndmask_b32_e64 v45, v45, v161, s[28:29]
	v_cndmask_b32_e64 v165, v165, 11, s[28:29]
	v_add_u32_sdwa v158, v173, v158 dst_sel:DWORD dst_unused:UNUSED_PAD src0_sel:WORD_1 src1_sel:DWORD
	v_add_u32_sdwa v159, v181, v159 dst_sel:DWORD dst_unused:UNUSED_PAD src0_sel:WORD_1 src1_sel:DWORD
	v_add_u32_sdwa v160, v189, v160 dst_sel:DWORD dst_unused:UNUSED_PAD src0_sel:WORD_1 src1_sel:DWORD
	v_add_u32_sdwa v161, v231, v161 dst_sel:DWORD dst_unused:UNUSED_PAD src0_sel:WORD_1 src1_sel:DWORD
	v_cmp_lt_u32_e64 s[4:5], v158, v238
	v_cmp_lt_u32_e64 s[6:7], v159, v239
	v_cmp_lt_u32_e64 s[8:9], v160, v240
	v_cmp_lt_u32_e64 s[28:29], v161, v241
	v_cndmask_b32_e64 v42, v42, v158, s[4:5]
	v_cndmask_b32_e64 v162, v162, 10, s[4:5]
	v_cndmask_b32_e64 v43, v43, v159, s[6:7]
	v_cndmask_b32_e64 v163, v163, 10, s[6:7]
	v_cndmask_b32_e64 v44, v44, v160, s[8:9]
	v_cndmask_b32_e64 v164, v164, 10, s[8:9]
	v_cndmask_b32_e64 v45, v45, v161, s[28:29]
	v_cndmask_b32_e64 v165, v165, 10, s[28:29]
	v_add_u32_sdwa v158, v173, v158 dst_sel:DWORD dst_unused:UNUSED_PAD src0_sel:WORD_0 src1_sel:DWORD
	v_add_u32_sdwa v159, v181, v159 dst_sel:DWORD dst_unused:UNUSED_PAD src0_sel:WORD_0 src1_sel:DWORD
	v_add_u32_sdwa v160, v189, v160 dst_sel:DWORD dst_unused:UNUSED_PAD src0_sel:WORD_0 src1_sel:DWORD
	v_add_u32_sdwa v161, v231, v161 dst_sel:DWORD dst_unused:UNUSED_PAD src0_sel:WORD_0 src1_sel:DWORD
	v_cmp_lt_u32_e64 s[4:5], v158, v238
	v_cmp_lt_u32_e64 s[6:7], v159, v239
	v_cmp_lt_u32_e64 s[8:9], v160, v240
	v_cmp_lt_u32_e64 s[28:29], v161, v241
	v_cndmask_b32_e64 v42, v42, v158, s[4:5]
	v_cndmask_b32_e64 v162, v162, 9, s[4:5]
	v_cndmask_b32_e64 v43, v43, v159, s[6:7]
	v_cndmask_b32_e64 v163, v163, 9, s[6:7]
	v_cndmask_b32_e64 v44, v44, v160, s[8:9]
; DI void idx_scan(const u32* hq, int need, u32* outbin, u32* outneed, int q, int lane) {
;     ...
;   if ((int)above < need && need <= (int)incl) {
;     u32 cum = above;
;     ...
;       u32 cnt = (hq[bin >> 1] >> ((bin & 1) * 16)) & 0xffffu;
;       if ((int)(cum + cnt) >= need) { outbin[q] = (u32)bin; outneed[q] = (u32)need - cum; break; }
;       cum += cnt;
;     }
	v_cndmask_b32_e64 v164, v164, 9, s[8:9]
	v_cndmask_b32_e64 v45, v45, v161, s[28:29]
	v_cndmask_b32_e64 v165, v165, 9, s[28:29]
	v_add_u32_sdwa v158, v172, v158 dst_sel:DWORD dst_unused:UNUSED_PAD src0_sel:WORD_1 src1_sel:DWORD
	v_add_u32_sdwa v159, v180, v159 dst_sel:DWORD dst_unused:UNUSED_PAD src0_sel:WORD_1 src1_sel:DWORD
	v_add_u32_sdwa v160, v188, v160 dst_sel:DWORD dst_unused:UNUSED_PAD src0_sel:WORD_1 src1_sel:DWORD
	v_add_u32_sdwa v161, v230, v161 dst_sel:DWORD dst_unused:UNUSED_PAD src0_sel:WORD_1 src1_sel:DWORD
	v_cmp_lt_u32_e64 s[4:5], v158, v238
	v_cmp_lt_u32_e64 s[6:7], v159, v239
	v_cmp_lt_u32_e64 s[8:9], v160, v240
	v_cmp_lt_u32_e64 s[28:29], v161, v241
	v_cndmask_b32_e64 v42, v42, v158, s[4:5]
	v_cndmask_b32_e64 v162, v162, 8, s[4:5]
	v_cndmask_b32_e64 v43, v43, v159, s[6:7]
	v_cndmask_b32_e64 v163, v163, 8, s[6:7]
	v_cndmask_b32_e64 v44, v44, v160, s[8:9]
	v_cndmask_b32_e64 v164, v164, 8, s[8:9]
	v_cndmask_b32_e64 v45, v45, v161, s[28:29]
	v_cndmask_b32_e64 v165, v165, 8, s[28:29]
	v_add_u32_sdwa v158, v172, v158 dst_sel:DWORD dst_unused:UNUSED_PAD src0_sel:WORD_0 src1_sel:DWORD
	v_add_u32_sdwa v159, v180, v159 dst_sel:DWORD dst_unused:UNUSED_PAD src0_sel:WORD_0 src1_sel:DWORD
	v_add_u32_sdwa v160, v188, v160 dst_sel:DWORD dst_unused:UNUSED_PAD src0_sel:WORD_0 src1_sel:DWORD
	v_add_u32_sdwa v161, v230, v161 dst_sel:DWORD dst_unused:UNUSED_PAD src0_sel:WORD_0 src1_sel:DWORD
	v_cmp_lt_u32_e64 s[4:5], v158, v238
	v_cmp_lt_u32_e64 s[6:7], v159, v239
	v_cmp_lt_u32_e64 s[8:9], v160, v240
	v_cmp_lt_u32_e64 s[28:29], v161, v241
	v_cndmask_b32_e64 v42, v42, v158, s[4:5]
	v_cndmask_b32_e64 v162, v162, 7, s[4:5]
	v_cndmask_b32_e64 v43, v43, v159, s[6:7]
	v_cndmask_b32_e64 v163, v163, 7, s[6:7]
	v_cndmask_b32_e64 v44, v44, v160, s[8:9]
	v_cndmask_b32_e64 v164, v164, 7, s[8:9]
	v_cndmask_b32_e64 v45, v45, v161, s[28:29]
	v_cndmask_b32_e64 v165, v165, 7, s[28:29]
	v_add_u32_sdwa v158, v171, v158 dst_sel:DWORD dst_unused:UNUSED_PAD src0_sel:WORD_1 src1_sel:DWORD
	v_add_u32_sdwa v159, v179, v159 dst_sel:DWORD dst_unused:UNUSED_PAD src0_sel:WORD_1 src1_sel:DWORD
	v_add_u32_sdwa v160, v187, v160 dst_sel:DWORD dst_unused:UNUSED_PAD src0_sel:WORD_1 src1_sel:DWORD
	v_add_u32_sdwa v161, v229, v161 dst_sel:DWORD dst_unused:UNUSED_PAD src0_sel:WORD_1 src1_sel:DWORD
	v_cmp_lt_u32_e64 s[4:5], v158, v238
	v_cmp_lt_u32_e64 s[6:7], v159, v239
	v_cmp_lt_u32_e64 s[8:9], v160, v240
	v_cmp_lt_u32_e64 s[28:29], v161, v241
	v_cndmask_b32_e64 v42, v42, v158, s[4:5]
	v_cndmask_b32_e64 v162, v162, 6, s[4:5]
	v_cndmask_b32_e64 v43, v43, v159, s[6:7]
	v_cndmask_b32_e64 v163, v163, 6, s[6:7]
	v_cndmask_b32_e64 v44, v44, v160, s[8:9]
	v_cndmask_b32_e64 v164, v164, 6, s[8:9]
	v_cndmask_b32_e64 v45, v45, v161, s[28:29]
	v_cndmask_b32_e64 v165, v165, 6, s[28:29]
	v_add_u32_sdwa v158, v171, v158 dst_sel:DWORD dst_unused:UNUSED_PAD src0_sel:WORD_0 src1_sel:DWORD
	v_add_u32_sdwa v159, v179, v159 dst_sel:DWORD dst_unused:UNUSED_PAD src0_sel:WORD_0 src1_sel:DWORD
	v_add_u32_sdwa v160, v187, v160 dst_sel:DWORD dst_unused:UNUSED_PAD src0_sel:WORD_0 src1_sel:DWORD
	v_add_u32_sdwa v161, v229, v161 dst_sel:DWORD dst_unused:UNUSED_PAD src0_sel:WORD_0 src1_sel:DWORD
	v_cmp_lt_u32_e64 s[4:5], v158, v238
	v_cmp_lt_u32_e64 s[6:7], v159, v239
	v_cmp_lt_u32_e64 s[8:9], v160, v240
	v_cmp_lt_u32_e64 s[28:29], v161, v241
	v_cndmask_b32_e64 v42, v42, v158, s[4:5]
	v_cndmask_b32_e64 v162, v162, 5, s[4:5]
	v_cndmask_b32_e64 v43, v43, v159, s[6:7]
	v_cndmask_b32_e64 v163, v163, 5, s[6:7]
	v_cndmask_b32_e64 v44, v44, v160, s[8:9]
	v_cndmask_b32_e64 v164, v164, 5, s[8:9]
	v_cndmask_b32_e64 v45, v45, v161, s[28:29]
	v_cndmask_b32_e64 v165, v165, 5, s[28:29]
	v_add_u32_sdwa v158, v170, v158 dst_sel:DWORD dst_unused:UNUSED_PAD src0_sel:WORD_1 src1_sel:DWORD
	v_add_u32_sdwa v159, v178, v159 dst_sel:DWORD dst_unused:UNUSED_PAD src0_sel:WORD_1 src1_sel:DWORD
	v_add_u32_sdwa v160, v186, v160 dst_sel:DWORD dst_unused:UNUSED_PAD src0_sel:WORD_1 src1_sel:DWORD
	v_add_u32_sdwa v161, v228, v161 dst_sel:DWORD dst_unused:UNUSED_PAD src0_sel:WORD_1 src1_sel:DWORD
	v_cmp_lt_u32_e64 s[4:5], v158, v238
	v_cmp_lt_u32_e64 s[6:7], v159, v239
	v_cmp_lt_u32_e64 s[8:9], v160, v240
	v_cmp_lt_u32_e64 s[28:29], v161, v241
	v_cndmask_b32_e64 v42, v42, v158, s[4:5]
	v_cndmask_b32_e64 v162, v162, 4, s[4:5]
	v_cndmask_b32_e64 v43, v43, v159, s[6:7]
	v_cndmask_b32_e64 v163, v163, 4, s[6:7]
	v_cndmask_b32_e64 v44, v44, v160, s[8:9]
	v_cndmask_b32_e64 v164, v164, 4, s[8:9]
	v_cndmask_b32_e64 v45, v45, v161, s[28:29]
	v_cndmask_b32_e64 v165, v165, 4, s[28:29]
	v_add_u32_sdwa v158, v170, v158 dst_sel:DWORD dst_unused:UNUSED_PAD src0_sel:WORD_0 src1_sel:DWORD
	v_add_u32_sdwa v159, v178, v159 dst_sel:DWORD dst_unused:UNUSED_PAD src0_sel:WORD_0 src1_sel:DWORD
	v_add_u32_sdwa v160, v186, v160 dst_sel:DWORD dst_unused:UNUSED_PAD src0_sel:WORD_0 src1_sel:DWORD
; DI void idx_scan(const u32* hq, int need, u32* outbin, u32* outneed, int q, int lane) {
;     ...
;   if ((int)above < need && need <= (int)incl) {
;     u32 cum = above;
;     ...
;       u32 cnt = (hq[bin >> 1] >> ((bin & 1) * 16)) & 0xffffu;
;       if ((int)(cum + cnt) >= need) { outbin[q] = (u32)bin; outneed[q] = (u32)need - cum; break; }
;       cum += cnt;
;     }
; DI void idx_job(const Params& p, int b, int qg, unsigned char* smem) {
;     ...
;   for (int qq = 0; qq < 4; ++qq) idx_scan(hist + (wave * 4 + qq) * 512, 256, binA, needB, wave * 4 + qq, lane);
;   __syncthreads();
;   for (int i = tid; i < 8192; i += 256) hist[i] = 0u;
;   __syncthreads();
	v_add_u32_sdwa v161, v228, v161 dst_sel:DWORD dst_unused:UNUSED_PAD src0_sel:WORD_0 src1_sel:DWORD
	v_cmp_lt_u32_e64 s[4:5], v158, v238
	v_cmp_lt_u32_e64 s[6:7], v159, v239
	v_cmp_lt_u32_e64 s[8:9], v160, v240
	v_cmp_lt_u32_e64 s[28:29], v161, v241
	v_cndmask_b32_e64 v42, v42, v158, s[4:5]
	v_cndmask_b32_e64 v162, v162, 3, s[4:5]
	v_cndmask_b32_e64 v43, v43, v159, s[6:7]
	v_cndmask_b32_e64 v163, v163, 3, s[6:7]
	v_cndmask_b32_e64 v44, v44, v160, s[8:9]
	v_cndmask_b32_e64 v164, v164, 3, s[8:9]
	v_cndmask_b32_e64 v45, v45, v161, s[28:29]
	v_cndmask_b32_e64 v165, v165, 3, s[28:29]
	v_add_u32_sdwa v158, v169, v158 dst_sel:DWORD dst_unused:UNUSED_PAD src0_sel:WORD_1 src1_sel:DWORD
	v_add_u32_sdwa v159, v177, v159 dst_sel:DWORD dst_unused:UNUSED_PAD src0_sel:WORD_1 src1_sel:DWORD
	v_add_u32_sdwa v160, v185, v160 dst_sel:DWORD dst_unused:UNUSED_PAD src0_sel:WORD_1 src1_sel:DWORD
	v_add_u32_sdwa v161, v227, v161 dst_sel:DWORD dst_unused:UNUSED_PAD src0_sel:WORD_1 src1_sel:DWORD
	v_cmp_lt_u32_e64 s[4:5], v158, v238
	v_cmp_lt_u32_e64 s[6:7], v159, v239
	v_cmp_lt_u32_e64 s[8:9], v160, v240
	v_cmp_lt_u32_e64 s[28:29], v161, v241
	v_cndmask_b32_e64 v42, v42, v158, s[4:5]
	v_cndmask_b32_e64 v162, v162, 2, s[4:5]
	v_cndmask_b32_e64 v43, v43, v159, s[6:7]
	v_cndmask_b32_e64 v163, v163, 2, s[6:7]
	v_cndmask_b32_e64 v44, v44, v160, s[8:9]
	v_cndmask_b32_e64 v164, v164, 2, s[8:9]
	v_cndmask_b32_e64 v45, v45, v161, s[28:29]
	v_cndmask_b32_e64 v165, v165, 2, s[28:29]
	v_add_u32_sdwa v158, v169, v158 dst_sel:DWORD dst_unused:UNUSED_PAD src0_sel:WORD_0 src1_sel:DWORD
	v_add_u32_sdwa v159, v177, v159 dst_sel:DWORD dst_unused:UNUSED_PAD src0_sel:WORD_0 src1_sel:DWORD
	v_add_u32_sdwa v160, v185, v160 dst_sel:DWORD dst_unused:UNUSED_PAD src0_sel:WORD_0 src1_sel:DWORD
	v_add_u32_sdwa v161, v227, v161 dst_sel:DWORD dst_unused:UNUSED_PAD src0_sel:WORD_0 src1_sel:DWORD
	v_cmp_lt_u32_e64 s[4:5], v158, v238
	v_cmp_lt_u32_e64 s[6:7], v159, v239
	v_cmp_lt_u32_e64 s[8:9], v160, v240
	v_cmp_lt_u32_e64 s[28:29], v161, v241
	v_cndmask_b32_e64 v42, v42, v158, s[4:5]
	v_cndmask_b32_e64 v162, v162, 1, s[4:5]
	v_cndmask_b32_e64 v43, v43, v159, s[6:7]
	v_cndmask_b32_e64 v163, v163, 1, s[6:7]
	v_cndmask_b32_e64 v44, v44, v160, s[8:9]
	v_cndmask_b32_e64 v164, v164, 1, s[8:9]
	v_cndmask_b32_e64 v45, v45, v161, s[28:29]
	v_cndmask_b32_e64 v165, v165, 1, s[28:29]
	v_add_u32_sdwa v158, v168, v158 dst_sel:DWORD dst_unused:UNUSED_PAD src0_sel:WORD_1 src1_sel:DWORD
	v_add_u32_sdwa v159, v176, v159 dst_sel:DWORD dst_unused:UNUSED_PAD src0_sel:WORD_1 src1_sel:DWORD
	v_add_u32_sdwa v160, v184, v160 dst_sel:DWORD dst_unused:UNUSED_PAD src0_sel:WORD_1 src1_sel:DWORD
	v_add_u32_sdwa v161, v226, v161 dst_sel:DWORD dst_unused:UNUSED_PAD src0_sel:WORD_1 src1_sel:DWORD
	v_cmp_lt_u32_e64 s[4:5], v158, v238
	v_cmp_lt_u32_e64 s[6:7], v159, v239
	v_cmp_lt_u32_e64 s[8:9], v160, v240
	v_cmp_lt_u32_e64 s[28:29], v161, v241
	v_cndmask_b32_e64 v42, v42, v158, s[4:5]
	v_cndmask_b32_e64 v162, v162, 0, s[4:5]
	v_cndmask_b32_e64 v43, v43, v159, s[6:7]
	v_cndmask_b32_e64 v163, v163, 0, s[6:7]
	v_cndmask_b32_e64 v44, v44, v160, s[8:9]
	v_cndmask_b32_e64 v164, v164, 0, s[8:9]
	v_cndmask_b32_e64 v45, v45, v161, s[28:29]
	v_cndmask_b32_e64 v165, v165, 0, s[28:29]
	v_add_u32_sdwa v158, v168, v158 dst_sel:DWORD dst_unused:UNUSED_PAD src0_sel:WORD_0 src1_sel:DWORD
	v_add_u32_sdwa v159, v176, v159 dst_sel:DWORD dst_unused:UNUSED_PAD src0_sel:WORD_0 src1_sel:DWORD
	v_add_u32_sdwa v160, v184, v160 dst_sel:DWORD dst_unused:UNUSED_PAD src0_sel:WORD_0 src1_sel:DWORD
	v_add_u32_sdwa v161, v226, v161 dst_sel:DWORD dst_unused:UNUSED_PAD src0_sel:WORD_0 src1_sel:DWORD
	v_cmp_lt_u32_e64 s[4:5], v158, v238
	v_cmp_lt_u32_e64 s[6:7], v159, v239
	v_cmp_lt_u32_e64 s[8:9], v160, v240
	v_cmp_lt_u32_e64 s[28:29], v161, v241
	v_cndmask_b32_e64 v42, v42, v158, s[4:5]
	v_cndmask_b32_e64 v162, v162, -1, s[4:5]
	v_cndmask_b32_e64 v43, v43, v159, s[6:7]
	v_cndmask_b32_e64 v163, v163, -1, s[6:7]
	v_cndmask_b32_e64 v44, v44, v160, s[8:9]
	v_cndmask_b32_e64 v164, v164, -1, s[8:9]
	v_cndmask_b32_e64 v45, v45, v161, s[28:29]
	v_cndmask_b32_e64 v165, v165, -1, s[28:29]
	v_lshl_add_u32 v50, v48, 4, v162
	v_lshl_add_u32 v51, v48, 4, v163
	v_lshl_add_u32 v52, v48, 4, v164
	v_lshl_add_u32 v53, v48, 4, v165
	v_sub_u32_e32 v54, v238, v42
	v_sub_u32_e32 v55, v239, v43
	v_sub_u32_e32 v242, v240, v44
	v_sub_u32_e32 v243, v241, v45
	s_mov_b64 exec, s[40:41]
	ds_write2_b32 v47, v50, v54 offset0:80 offset1:96
	s_mov_b64 exec, s[42:43]
	ds_write2_b32 v47, v51, v55 offset0:81 offset1:97
	s_mov_b64 exec, s[44:45]
	ds_write2_b32 v47, v52, v242 offset0:82 offset1:98
	s_mov_b64 exec, s[46:47]
	ds_write2_b32 v47, v53, v243 offset0:83 offset1:99
	s_mov_b64 exec, -1
	s_movk_i32 s2, 0x2000
	v_cmp_gt_i32_e64 s[4:5], s2, v86
	s_waitcnt lgkmcnt(0)
	s_barrier
	s_and_saveexec_b64 s[2:3], s[4:5]
	s_cbranch_execz .LBB0_602
	s_mov_b64 s[6:7], 0

; template <int PASS>
; DI void idx_pass(const u16* kp, const bf16x8 (&qf)[8], const float (&wq)[8], int wave, int ntile, int lm, int lg, int tq, bool selall,
;                  u32 bA, u32 pfx, u32* hist, u32* maskw, u32* cand, u32* ccnt) {
;   auto ldk = [&](int t) { return *(const bf16x8*)(kp + (size_t)(t < ntile ? t : 0) * 512); };
;   int kt = wave;
;   bf16x8 ka = ldk(kt), kb = ldk(kt + 4);
;   for (; kt + 4 < ntile - 1; kt += 8) {
; DI void idx_job(const Params& p, int b, int qg, unsigned char* smem) {
;     ...
;   __syncthreads();
;   idx_pass<1>(kp, qf, wq, wave, ntile, lm, lg, tq, selall, binA[lm], 0u, hist, maskw, cand, ccnt);
.LBB0_602:
	s_or_b64 exec, exec, s[2:3]
	s_waitcnt lgkmcnt(0)
	s_barrier
	s_cbranch_vccnz .Lidx1_pj
	global_load_dwordx4 v[42:45], v[92:93], off
	global_load_dwordx4 v[46:49], v[94:95], off

; template <int PASS, bool DIAG>
; DI void idx_tile(const bf16x8 kf, const bf16x8 (&qf)[8], const float (&wq)[8], int kt, int lm, int lg, int tq, bool selall, u32 bA, u32 pfx,
;                  u32* hist, u32* maskw, u32* cand, u32* ccnt) {
;     ...
;     } else if (PASS == 1) {
;       if (valid && (u >> 22) == bA) { const u32 bin = (u >> 12) & 1023u; atomicAdd(&hist[lm * 512 + (bin >> 1)], 1u << ((bin & 1) * 16)); }
; template <int PASS>
; DI void idx_pass(const u16* kp, const bf16x8 (&qf)[8], const float (&wq)[8], int wave, int ntile, int lm, int lg, int tq, bool selall,
;                  u32 bA, u32 pfx, u32* hist, u32* maskw, u32* cand, u32* ccnt) {
;     ...
;   for (; kt + 4 < ntile - 1; kt += 8) {
;     const bf16x8 kc = ldk(kt + 8), kd = ldk(kt + 12);
;     idx_tile<PASS, false>(ka, qf, wq, kt, lm, lg, tq, selall, bA, pfx, hist, maskw, cand, ccnt);
;     idx_tile<PASS, false>(kb, qf, wq, kt + 4, lm, lg, tq, selall, bA, pfx, hist, maskw, cand, ccnt);
;     ka = kc; kb = kd;
.Lidx1_loop:
	s_waitcnt vmcnt(2)
	v_mov_b64_e32 v[82:83], v[110:111]
	v_mov_b64_e32 v[84:85], v[112:113]
	v_mov_b64_e32 v[46:47], v[114:115]
	v_mov_b64_e32 v[48:49], v[116:117]
	global_load_dwordx4 v[110:113], v134, s[90:91]
	global_load_dwordx4 v[114:117], v134, s[92:93]
	v_add_u32_e32 v134, 0x2000, v134
	v_ashrrev_i32_e32 v58, 31, v82
	v_bitop3_b32 v54, v58, v82, s39 bitop3:0x36
	v_lshrrev_b32_e32 v58, 22, v54
	v_cmp_eq_u32_e64 s[4:5], v58, v137
	s_and_saveexec_b64 s[8:9], s[4:5]
	s_cbranch_execz .Lidx1_skip0
	v_lshrrev_b32_e32 v58, 8, v54
	v_lshrrev_b32_e32 v54, 11, v54
	v_and_b32_e32 v58, 16, v58
	v_and_b32_e32 v54, 0x7fc, v54
	v_lshlrev_b32_e64 v58, v58, 1
	v_add_u32_e32 v54, v154, v54
	ds_add_u32 v54, v58

; template <int PASS, bool DIAG>
; DI void idx_tile(const bf16x8 kf, const bf16x8 (&qf)[8], const float (&wq)[8], int kt, int lm, int lg, int tq, bool selall, u32 bA, u32 pfx,
;                  u32* hist, u32* maskw, u32* cand, u32* ccnt) {
;     ...
;     } else if (PASS == 1) {
;       if (valid && (u >> 22) == bA) { const u32 bin = (u >> 12) & 1023u; atomicAdd(&hist[lm * 512 + (bin >> 1)], 1u << ((bin & 1) * 16)); }
; template <int PASS>
; DI void idx_pass(const u16* kp, const bf16x8 (&qf)[8], const float (&wq)[8], int wave, int ntile, int lm, int lg, int tq, bool selall,
;                  u32 bA, u32 pfx, u32* hist, u32* maskw, u32* cand, u32* ccnt) {
;     ...
;   for (; kt + 4 < ntile - 1; kt += 8) {
;     const bf16x8 kc = ldk(kt + 8), kd = ldk(kt + 12);
;     idx_tile<PASS, false>(ka, qf, wq, kt, lm, lg, tq, selall, bA, pfx, hist, maskw, cand, ccnt);
;     idx_tile<PASS, false>(kb, qf, wq, kt + 4, lm, lg, tq, selall, bA, pfx, hist, maskw, cand, ccnt);
;     ka = kc; kb = kd;
.Lidx1_skip7:
	s_or_b64 exec, exec, s[8:9]
	s_add_i32 s88, s88, 8
	s_add_i32 s4, s88, 4
	s_cmp_ge_i32 s4, s89
	s_cbranch_scc1 .Lidx1_done
	s_waitcnt vmcnt(2)
	v_mov_b64_e32 v[82:83], v[118:119]
	v_mov_b64_e32 v[84:85], v[120:121]
	v_mov_b64_e32 v[46:47], v[122:123]
	v_mov_b64_e32 v[48:49], v[124:125]
	global_load_dwordx4 v[118:121], v134, s[90:91]
	global_load_dwordx4 v[122:125], v134, s[92:93]
	v_add_u32_e32 v134, 0x2000, v134
	v_ashrrev_i32_e32 v58, 31, v82
	v_bitop3_b32 v54, v58, v82, s39 bitop3:0x36
	v_lshrrev_b32_e32 v58, 22, v54
	v_cmp_eq_u32_e64 s[4:5], v58, v137
	s_and_saveexec_b64 s[8:9], s[4:5]
	s_cbranch_execz .Lidx1_skip8
	v_lshrrev_b32_e32 v58, 8, v54
	v_lshrrev_b32_e32 v54, 11, v54
	v_and_b32_e32 v58, 16, v58
	v_and_b32_e32 v54, 0x7fc, v54
	v_lshlrev_b32_e64 v58, v58, 1
	v_add_u32_e32 v54, v154, v54
	ds_add_u32 v54, v58

; template <int PASS>
; DI void idx_pass(const u16* kp, const bf16x8 (&qf)[8], const float (&wq)[8], int wave, int ntile, int lm, int lg, int tq, bool selall,
;                  u32 bA, u32 pfx, u32* hist, u32* maskw, u32* cand, u32* ccnt) {
;     ...
;   }
;   if (kt < ntile - 1) { idx_tile<PASS, false>(ka, qf, wq, kt, lm, lg, tq, selall, bA, pfx, hist, maskw, cand, ccnt); kt += 4; ka = kb; }
;   if (kt == ntile - 1) idx_tile<PASS, true>(ka, qf, wq, kt, lm, lg, tq, selall, bA, pfx, hist, maskw, cand, ccnt);
.Lidx1_done:
	s_waitcnt vmcnt(0)
	v_mov_b64_e32 v[42:43], v[126:127]
	v_mov_b64_e32 v[44:45], v[128:129]
	v_mov_b64_e32 v[46:47], v[130:131]
	v_mov_b64_e32 v[48:49], v[132:133]
	v_mov_b32_e32 v153, s88
	v_add_u32_e32 v79, 4, v153

; DI void idx_scan(const u32* hq, int need, u32* outbin, u32* outneed, int q, int lane) {
;   u32 c = 0;
; #pragma unroll
;   for (int w = 0; w < 8; ++w) { u32 v = hq[8 * lane + w]; c += (v & 0xffffu) + (v >> 16); }
;   u32 incl = c;
; #pragma unroll
;   for (int o = 1; o < 64; o <<= 1) { u32 v = __shfl_down(incl, o); if (lane + o < 64) incl += v; }
;   const u32 above = incl - c;
;   if ((int)above < need && need <= (int)incl) {
; DI void idx_job(const Params& p, int b, int qg, unsigned char* smem) {
;     ...
;   for (int qq = 0; qq < 4; ++qq) idx_scan(hist + (wave * 4 + qq) * 512, (int)needB[wave * 4 + qq], binB, needC, wave * 4 + qq, lane);
.LBB0_641:
	s_or_b64 exec, exec, s[2:3]
	s_waitcnt lgkmcnt(0)
	s_barrier
	s_waitcnt vmcnt(0)
	s_cbranch_vccz .Lidx2_ne
	v_sub_u32_e32 v160, v97, v109
	v_subrev_u32_e32 v160, 5, v160
	v_and_b32_e32 v160, -8, v160
	v_add_u32_e32 v160, v160, v109
	v_add_u32_e32 v162, 12, v160
	v_add_u32_e32 v160, 8, v160
	v_cmp_le_i32_e64 s[4:5], v160, v97
	v_cmp_le_i32_e64 s[8:9], v162, v97
	v_mov_b32_e32 v161, 0
	v_mov_b32_e32 v163, 0
	v_cndmask_b32_e64 v160, 0, v160, s[4:5]
	v_cndmask_b32_e64 v162, 0, v162, s[8:9]
	v_lshlrev_b64 v[160:161], 10, v[160:161]
	v_lshlrev_b64 v[162:163], 10, v[162:163]
	v_lshl_add_u64 v[160:161], v[90:91], 0, v[160:161]
	v_lshl_add_u64 v[162:163], v[90:91], 0, v[162:163]
	global_load_dwordx4 v[126:129], v[160:161], off
	global_load_dwordx4 v[130:133], v[162:163], off
	v_lshl_add_u32 v134, v109, 10, v250
	s_add_u32 s92, s90, 0x1000
	s_addc_u32 s93, s91, 0
	v_readfirstlane_b32 s88, v109
	v_readfirstlane_b32 s89, v97
	global_load_dwordx4 v[110:113], v134, s[90:91]
	global_load_dwordx4 v[114:117], v134, s[92:93]
	v_add_u32_e32 v135, 0x2000, v134
	global_load_dwordx4 v[118:121], v135, s[90:91]
	global_load_dwordx4 v[122:125], v135, s[92:93]
	v_add_u32_e32 v134, 0x4000, v134
.Lidx2_ne:
	v_lshl_add_u32 v46, v109, 13, v96
	v_and_b32_e32 v48, 63, v207
	v_lshl_add_u32 v47, v109, 4, v96
	v_lshl_add_u32 v46, v48, 5, v46
	v_add_u32_e32 v47, 0xc000, v47
	ds_read_b128 v[168:171], v46
	ds_read_b128 v[172:175], v46 offset:16
	ds_read_b128 v[176:179], v46 offset:2048
	ds_read_b128 v[180:183], v46 offset:2064
	ds_read_b128 v[184:187], v46 offset:4096
	ds_read_b128 v[188:191], v46 offset:4112
	ds_read_b128 v[226:229], v46 offset:6144
	ds_read_b128 v[230:233], v46 offset:6160
	ds_read_b128 v[238:241], v47 offset:384
	s_waitcnt lgkmcnt(0)
	v_add3_u32 v192, v168, v169, v170
	v_add3_u32 v193, v176, v177, v178
	v_add3_u32 v194, v184, v185, v186
	v_add3_u32 v195, v226, v227, v228
	v_add3_u32 v192, v192, v171, v172
	v_add3_u32 v193, v193, v179, v180
	v_add3_u32 v194, v194, v187, v188
	v_add3_u32 v195, v195, v229, v230
	v_add3_u32 v192, v192, v173, v174
	v_add3_u32 v193, v193, v181, v182
	v_add3_u32 v194, v194, v189, v190
	v_add3_u32 v195, v195, v231, v232
	v_add_u32_e32 v192, v192, v175
	v_add_u32_e32 v193, v193, v183
	v_add_u32_e32 v194, v194, v191
	v_add_u32_e32 v195, v195, v233
	v_add_u32_sdwa v192, v192, v192 dst_sel:DWORD dst_unused:UNUSED_PAD src0_sel:WORD_0 src1_sel:WORD_1
	v_add_u32_sdwa v193, v193, v193 dst_sel:DWORD dst_unused:UNUSED_PAD src0_sel:WORD_0 src1_sel:WORD_1
	v_add_u32_sdwa v194, v194, v194 dst_sel:DWORD dst_unused:UNUSED_PAD src0_sel:WORD_0 src1_sel:WORD_1
	v_add_u32_sdwa v195, v195, v195 dst_sel:DWORD dst_unused:UNUSED_PAD src0_sel:WORD_0 src1_sel:WORD_1
	v_mov_b32_e32 v234, v192
	v_mov_b32_e32 v235, v193
	v_mov_b32_e32 v236, v194
	v_mov_b32_e32 v237, v195
	v_add_u32_dpp v234, v234, v234 row_shl:1 row_mask:0xf bank_mask:0xf
	v_add_u32_dpp v235, v235, v235 row_shl:1 row_mask:0xf bank_mask:0xf
	v_add_u32_dpp v236, v236, v236 row_shl:1 row_mask:0xf bank_mask:0xf
	v_add_u32_dpp v237, v237, v237 row_shl:1 row_mask:0xf bank_mask:0xf
	v_add_u32_dpp v234, v234, v234 row_shl:2 row_mask:0xf bank_mask:0xf
	v_add_u32_dpp v235, v235, v235 row_shl:2 row_mask:0xf bank_mask:0xf
	v_add_u32_dpp v236, v236, v236 row_shl:2 row_mask:0xf bank_mask:0xf
	v_add_u32_dpp v237, v237, v237 row_shl:2 row_mask:0xf bank_mask:0xf
	v_add_u32_dpp v234, v234, v234 row_shl:4 row_mask:0xf bank_mask:0xf
	v_add_u32_dpp v235, v235, v235 row_shl:4 row_mask:0xf bank_mask:0xf
	v_add_u32_dpp v236, v236, v236 row_shl:4 row_mask:0xf bank_mask:0xf
	v_add_u32_dpp v237, v237, v237 row_shl:4 row_mask:0xf bank_mask:0xf
	v_add_u32_dpp v234, v234, v234 row_shl:8 row_mask:0xf bank_mask:0xf
	v_add_u32_dpp v235, v235, v235 row_shl:8 row_mask:0xf bank_mask:0xf
	v_add_u32_dpp v236, v236, v236 row_shl:8 row_mask:0xf bank_mask:0xf
	v_add_u32_dpp v237, v237, v237 row_shl:8 row_mask:0xf bank_mask:0xf
	s_nop 1
	v_readlane_b32 s40, v234, 16
	v_readlane_b32 s41, v234, 32
	v_readlane_b32 s42, v234, 48
	v_readlane_b32 s43, v235, 16
	v_readlane_b32 s44, v235, 32
	v_readlane_b32 s45, v235, 48
	v_readlane_b32 s46, v236, 16
	v_readlane_b32 s47, v236, 32
	v_readlane_b32 s48, v236, 48
	v_readlane_b32 s49, v237, 16
	v_readlane_b32 s50, v237, 32
	v_readlane_b32 s51, v237, 48
	s_nop 0
	s_add_i32 s41, s41, s42
	s_add_i32 s40, s40, s41
	s_add_i32 s44, s44, s45
	s_add_i32 s43, s43, s44
	s_add_i32 s47, s47, s48
	s_add_i32 s46, s46, s47
	s_add_i32 s50, s50, s51
	s_add_i32 s49, s49, s50
	s_mov_b32 exec_lo, 0xffff
	s_mov_b32 exec_hi, 0
	v_add_u32_e32 v234, s40, v234
	v_add_u32_e32 v235, s43, v235
	v_add_u32_e32 v236, s46, v236
	v_add_u32_e32 v237, s49, v237
	s_mov_b32 exec_lo, 0xffff0000
	v_add_u32_e32 v234, s41, v234
	v_add_u32_e32 v235, s44, v235
	v_add_u32_e32 v236, s47, v236
	v_add_u32_e32 v237, s50, v237
	s_mov_b32 exec_lo, 0
	s_mov_b32 exec_hi, 0xffff
	v_add_u32_e32 v234, s42, v234
	v_add_u32_e32 v235, s45, v235
	v_add_u32_e32 v236, s48, v236
	v_add_u32_e32 v237, s51, v237
	s_mov_b64 exec, -1
	v_sub_u32_e32 v158, v234, v192
	v_sub_u32_e32 v159, v235, v193
	v_sub_u32_e32 v160, v236, v194
	v_sub_u32_e32 v161, v237, v195
	v_cmp_lt_u32_e64 s[4:5], v158, v238
	v_cmp_lt_u32_e64 s[6:7], v159, v239
	v_cmp_lt_u32_e64 s[8:9], v160, v240
	v_cmp_lt_u32_e64 s[28:29], v161, v241
	v_cmp_le_u32_e64 s[40:41], v238, v234
	v_cmp_le_u32_e64 s[42:43], v239, v235
	v_cmp_le_u32_e64 s[44:45], v240, v236
	v_cmp_le_u32_e64 s[46:47], v241, v237
	v_mov_b32_e32 v42, v158
	v_mov_b32_e32 v43, v159
	v_mov_b32_e32 v44, v160
	v_mov_b32_e32 v45, v161
	v_mov_b32_e32 v162, 15
	v_mov_b32_e32 v163, 15
	v_mov_b32_e32 v164, 15
	v_mov_b32_e32 v165, 15
; DI void idx_scan(const u32* hq, int need, u32* outbin, u32* outneed, int q, int lane) {
;     ...
;   if ((int)above < need && need <= (int)incl) {
;     u32 cum = above;
;     ...
;       u32 cnt = (hq[bin >> 1] >> ((bin & 1) * 16)) & 0xffffu;
;       if ((int)(cum + cnt) >= need) { outbin[q] = (u32)bin; outneed[q] = (u32)need - cum; break; }
;       cum += cnt;
;     }
	s_and_b64 s[40:41], s[40:41], s[4:5]
	s_and_b64 s[42:43], s[42:43], s[6:7]
	s_and_b64 s[44:45], s[44:45], s[8:9]
	s_and_b64 s[46:47], s[46:47], s[28:29]
	v_add_u32_sdwa v158, v175, v158 dst_sel:DWORD dst_unused:UNUSED_PAD src0_sel:WORD_1 src1_sel:DWORD
	v_add_u32_sdwa v159, v183, v159 dst_sel:DWORD dst_unused:UNUSED_PAD src0_sel:WORD_1 src1_sel:DWORD
	v_add_u32_sdwa v160, v191, v160 dst_sel:DWORD dst_unused:UNUSED_PAD src0_sel:WORD_1 src1_sel:DWORD
	v_add_u32_sdwa v161, v233, v161 dst_sel:DWORD dst_unused:UNUSED_PAD src0_sel:WORD_1 src1_sel:DWORD
	v_cmp_lt_u32_e64 s[4:5], v158, v238
	v_cmp_lt_u32_e64 s[6:7], v159, v239
	v_cmp_lt_u32_e64 s[8:9], v160, v240
	v_cmp_lt_u32_e64 s[28:29], v161, v241
	v_cndmask_b32_e64 v42, v42, v158, s[4:5]
	v_cndmask_b32_e64 v162, v162, 14, s[4:5]
	v_cndmask_b32_e64 v43, v43, v159, s[6:7]
	v_cndmask_b32_e64 v163, v163, 14, s[6:7]
	v_cndmask_b32_e64 v44, v44, v160, s[8:9]
	v_cndmask_b32_e64 v164, v164, 14, s[8:9]
	v_cndmask_b32_e64 v45, v45, v161, s[28:29]
	v_cndmask_b32_e64 v165, v165, 14, s[28:29]
	v_add_u32_sdwa v158, v175, v158 dst_sel:DWORD dst_unused:UNUSED_PAD src0_sel:WORD_0 src1_sel:DWORD
	v_add_u32_sdwa v159, v183, v159 dst_sel:DWORD dst_unused:UNUSED_PAD src0_sel:WORD_0 src1_sel:DWORD
	v_add_u32_sdwa v160, v191, v160 dst_sel:DWORD dst_unused:UNUSED_PAD src0_sel:WORD_0 src1_sel:DWORD
	v_add_u32_sdwa v161, v233, v161 dst_sel:DWORD dst_unused:UNUSED_PAD src0_sel:WORD_0 src1_sel:DWORD
	v_cmp_lt_u32_e64 s[4:5], v158, v238
	v_cmp_lt_u32_e64 s[6:7], v159, v239
	v_cmp_lt_u32_e64 s[8:9], v160, v240
	v_cmp_lt_u32_e64 s[28:29], v161, v241
	v_cndmask_b32_e64 v42, v42, v158, s[4:5]
	v_cndmask_b32_e64 v162, v162, 13, s[4:5]
	v_cndmask_b32_e64 v43, v43, v159, s[6:7]
	v_cndmask_b32_e64 v163, v163, 13, s[6:7]
	v_cndmask_b32_e64 v44, v44, v160, s[8:9]
	v_cndmask_b32_e64 v164, v164, 13, s[8:9]
	v_cndmask_b32_e64 v45, v45, v161, s[28:29]
	v_cndmask_b32_e64 v165, v165, 13, s[28:29]
	v_add_u32_sdwa v158, v174, v158 dst_sel:DWORD dst_unused:UNUSED_PAD src0_sel:WORD_1 src1_sel:DWORD
	v_add_u32_sdwa v159, v182, v159 dst_sel:DWORD dst_unused:UNUSED_PAD src0_sel:WORD_1 src1_sel:DWORD
	v_add_u32_sdwa v160, v190, v160 dst_sel:DWORD dst_unused:UNUSED_PAD src0_sel:WORD_1 src1_sel:DWORD
	v_add_u32_sdwa v161, v232, v161 dst_sel:DWORD dst_unused:UNUSED_PAD src0_sel:WORD_1 src1_sel:DWORD
	v_cmp_lt_u32_e64 s[4:5], v158, v238
	v_cmp_lt_u32_e64 s[6:7], v159, v239
	v_cmp_lt_u32_e64 s[8:9], v160, v240
	v_cmp_lt_u32_e64 s[28:29], v161, v241
	v_cndmask_b32_e64 v42, v42, v158, s[4:5]
	v_cndmask_b32_e64 v162, v162, 12, s[4:5]
	v_cndmask_b32_e64 v43, v43, v159, s[6:7]
	v_cndmask_b32_e64 v163, v163, 12, s[6:7]
	v_cndmask_b32_e64 v44, v44, v160, s[8:9]
	v_cndmask_b32_e64 v164, v164, 12, s[8:9]
	v_cndmask_b32_e64 v45, v45, v161, s[28:29]
	v_cndmask_b32_e64 v165, v165, 12, s[28:29]
	v_add_u32_sdwa v158, v174, v158 dst_sel:DWORD dst_unused:UNUSED_PAD src0_sel:WORD_0 src1_sel:DWORD
	v_add_u32_sdwa v159, v182, v159 dst_sel:DWORD dst_unused:UNUSED_PAD src0_sel:WORD_0 src1_sel:DWORD
	v_add_u32_sdwa v160, v190, v160 dst_sel:DWORD dst_unused:UNUSED_PAD src0_sel:WORD_0 src1_sel:DWORD
	v_add_u32_sdwa v161, v232, v161 dst_sel:DWORD dst_unused:UNUSED_PAD src0_sel:WORD_0 src1_sel:DWORD
	v_cmp_lt_u32_e64 s[4:5], v158, v238
	v_cmp_lt_u32_e64 s[6:7], v159, v239
	v_cmp_lt_u32_e64 s[8:9], v160, v240
	v_cmp_lt_u32_e64 s[28:29], v161, v241
	v_cndmask_b32_e64 v42, v42, v158, s[4:5]
	v_cndmask_b32_e64 v162, v162, 11, s[4:5]
	v_cndmask_b32_e64 v43, v43, v159, s[6:7]
	v_cndmask_b32_e64 v163, v163, 11, s[6:7]
	v_cndmask_b32_e64 v44, v44, v160, s[8:9]
	v_cndmask_b32_e64 v164, v164, 11, s[8:9]
	v_cndmask_b32_e64 v45, v45, v161, s[28:29]
	v_cndmask_b32_e64 v165, v165, 11, s[28:29]
	v_add_u32_sdwa v158, v173, v158 dst_sel:DWORD dst_unused:UNUSED_PAD src0_sel:WORD_1 src1_sel:DWORD
	v_add_u32_sdwa v159, v181, v159 dst_sel:DWORD dst_unused:UNUSED_PAD src0_sel:WORD_1 src1_sel:DWORD
	v_add_u32_sdwa v160, v189, v160 dst_sel:DWORD dst_unused:UNUSED_PAD src0_sel:WORD_1 src1_sel:DWORD
	v_add_u32_sdwa v161, v231, v161 dst_sel:DWORD dst_unused:UNUSED_PAD src0_sel:WORD_1 src1_sel:DWORD
	v_cmp_lt_u32_e64 s[4:5], v158, v238
	v_cmp_lt_u32_e64 s[6:7], v159, v239
	v_cmp_lt_u32_e64 s[8:9], v160, v240
	v_cmp_lt_u32_e64 s[28:29], v161, v241
	v_cndmask_b32_e64 v42, v42, v158, s[4:5]
	v_cndmask_b32_e64 v162, v162, 10, s[4:5]
	v_cndmask_b32_e64 v43, v43, v159, s[6:7]
	v_cndmask_b32_e64 v163, v163, 10, s[6:7]
	v_cndmask_b32_e64 v44, v44, v160, s[8:9]
	v_cndmask_b32_e64 v164, v164, 10, s[8:9]
	v_cndmask_b32_e64 v45, v45, v161, s[28:29]
	v_cndmask_b32_e64 v165, v165, 10, s[28:29]
	v_add_u32_sdwa v158, v173, v158 dst_sel:DWORD dst_unused:UNUSED_PAD src0_sel:WORD_0 src1_sel:DWORD
	v_add_u32_sdwa v159, v181, v159 dst_sel:DWORD dst_unused:UNUSED_PAD src0_sel:WORD_0 src1_sel:DWORD
	v_add_u32_sdwa v160, v189, v160 dst_sel:DWORD dst_unused:UNUSED_PAD src0_sel:WORD_0 src1_sel:DWORD
	v_add_u32_sdwa v161, v231, v161 dst_sel:DWORD dst_unused:UNUSED_PAD src0_sel:WORD_0 src1_sel:DWORD
	v_cmp_lt_u32_e64 s[4:5], v158, v238
	v_cmp_lt_u32_e64 s[6:7], v159, v239
	v_cmp_lt_u32_e64 s[8:9], v160, v240
	v_cmp_lt_u32_e64 s[28:29], v161, v241
	v_cndmask_b32_e64 v42, v42, v158, s[4:5]
	v_cndmask_b32_e64 v162, v162, 9, s[4:5]
	v_cndmask_b32_e64 v43, v43, v159, s[6:7]
	v_cndmask_b32_e64 v163, v163, 9, s[6:7]
	v_cndmask_b32_e64 v44, v44, v160, s[8:9]
	v_cndmask_b32_e64 v164, v164, 9, s[8:9]
	v_cndmask_b32_e64 v45, v45, v161, s[28:29]
	v_cndmask_b32_e64 v165, v165, 9, s[28:29]
	v_add_u32_sdwa v158, v172, v158 dst_sel:DWORD dst_unused:UNUSED_PAD src0_sel:WORD_1 src1_sel:DWORD
; DI void idx_scan(const u32* hq, int need, u32* outbin, u32* outneed, int q, int lane) {
;     ...
;   if ((int)above < need && need <= (int)incl) {
;     u32 cum = above;
;     ...
;       u32 cnt = (hq[bin >> 1] >> ((bin & 1) * 16)) & 0xffffu;
;       if ((int)(cum + cnt) >= need) { outbin[q] = (u32)bin; outneed[q] = (u32)need - cum; break; }
;       cum += cnt;
;     }
	v_add_u32_sdwa v159, v180, v159 dst_sel:DWORD dst_unused:UNUSED_PAD src0_sel:WORD_1 src1_sel:DWORD
	v_add_u32_sdwa v160, v188, v160 dst_sel:DWORD dst_unused:UNUSED_PAD src0_sel:WORD_1 src1_sel:DWORD
	v_add_u32_sdwa v161, v230, v161 dst_sel:DWORD dst_unused:UNUSED_PAD src0_sel:WORD_1 src1_sel:DWORD
	v_cmp_lt_u32_e64 s[4:5], v158, v238
	v_cmp_lt_u32_e64 s[6:7], v159, v239
	v_cmp_lt_u32_e64 s[8:9], v160, v240
	v_cmp_lt_u32_e64 s[28:29], v161, v241
	v_cndmask_b32_e64 v42, v42, v158, s[4:5]
	v_cndmask_b32_e64 v162, v162, 8, s[4:5]
	v_cndmask_b32_e64 v43, v43, v159, s[6:7]
	v_cndmask_b32_e64 v163, v163, 8, s[6:7]
	v_cndmask_b32_e64 v44, v44, v160, s[8:9]
	v_cndmask_b32_e64 v164, v164, 8, s[8:9]
	v_cndmask_b32_e64 v45, v45, v161, s[28:29]
	v_cndmask_b32_e64 v165, v165, 8, s[28:29]
	v_add_u32_sdwa v158, v172, v158 dst_sel:DWORD dst_unused:UNUSED_PAD src0_sel:WORD_0 src1_sel:DWORD
	v_add_u32_sdwa v159, v180, v159 dst_sel:DWORD dst_unused:UNUSED_PAD src0_sel:WORD_0 src1_sel:DWORD
	v_add_u32_sdwa v160, v188, v160 dst_sel:DWORD dst_unused:UNUSED_PAD src0_sel:WORD_0 src1_sel:DWORD
	v_add_u32_sdwa v161, v230, v161 dst_sel:DWORD dst_unused:UNUSED_PAD src0_sel:WORD_0 src1_sel:DWORD
	v_cmp_lt_u32_e64 s[4:5], v158, v238
	v_cmp_lt_u32_e64 s[6:7], v159, v239
	v_cmp_lt_u32_e64 s[8:9], v160, v240
	v_cmp_lt_u32_e64 s[28:29], v161, v241
	v_cndmask_b32_e64 v42, v42, v158, s[4:5]
	v_cndmask_b32_e64 v162, v162, 7, s[4:5]
	v_cndmask_b32_e64 v43, v43, v159, s[6:7]
	v_cndmask_b32_e64 v163, v163, 7, s[6:7]
	v_cndmask_b32_e64 v44, v44, v160, s[8:9]
	v_cndmask_b32_e64 v164, v164, 7, s[8:9]
	v_cndmask_b32_e64 v45, v45, v161, s[28:29]
	v_cndmask_b32_e64 v165, v165, 7, s[28:29]
	v_add_u32_sdwa v158, v171, v158 dst_sel:DWORD dst_unused:UNUSED_PAD src0_sel:WORD_1 src1_sel:DWORD
	v_add_u32_sdwa v159, v179, v159 dst_sel:DWORD dst_unused:UNUSED_PAD src0_sel:WORD_1 src1_sel:DWORD
	v_add_u32_sdwa v160, v187, v160 dst_sel:DWORD dst_unused:UNUSED_PAD src0_sel:WORD_1 src1_sel:DWORD
	v_add_u32_sdwa v161, v229, v161 dst_sel:DWORD dst_unused:UNUSED_PAD src0_sel:WORD_1 src1_sel:DWORD
	v_cmp_lt_u32_e64 s[4:5], v158, v238
	v_cmp_lt_u32_e64 s[6:7], v159, v239
	v_cmp_lt_u32_e64 s[8:9], v160, v240
	v_cmp_lt_u32_e64 s[28:29], v161, v241
	v_cndmask_b32_e64 v42, v42, v158, s[4:5]
	v_cndmask_b32_e64 v162, v162, 6, s[4:5]
	v_cndmask_b32_e64 v43, v43, v159, s[6:7]
	v_cndmask_b32_e64 v163, v163, 6, s[6:7]
	v_cndmask_b32_e64 v44, v44, v160, s[8:9]
	v_cndmask_b32_e64 v164, v164, 6, s[8:9]
	v_cndmask_b32_e64 v45, v45, v161, s[28:29]
	v_cndmask_b32_e64 v165, v165, 6, s[28:29]
	v_add_u32_sdwa v158, v171, v158 dst_sel:DWORD dst_unused:UNUSED_PAD src0_sel:WORD_0 src1_sel:DWORD
	v_add_u32_sdwa v159, v179, v159 dst_sel:DWORD dst_unused:UNUSED_PAD src0_sel:WORD_0 src1_sel:DWORD
	v_add_u32_sdwa v160, v187, v160 dst_sel:DWORD dst_unused:UNUSED_PAD src0_sel:WORD_0 src1_sel:DWORD
	v_add_u32_sdwa v161, v229, v161 dst_sel:DWORD dst_unused:UNUSED_PAD src0_sel:WORD_0 src1_sel:DWORD
	v_cmp_lt_u32_e64 s[4:5], v158, v238
	v_cmp_lt_u32_e64 s[6:7], v159, v239
	v_cmp_lt_u32_e64 s[8:9], v160, v240
	v_cmp_lt_u32_e64 s[28:29], v161, v241
	v_cndmask_b32_e64 v42, v42, v158, s[4:5]
	v_cndmask_b32_e64 v162, v162, 5, s[4:5]
	v_cndmask_b32_e64 v43, v43, v159, s[6:7]
	v_cndmask_b32_e64 v163, v163, 5, s[6:7]
	v_cndmask_b32_e64 v44, v44, v160, s[8:9]
	v_cndmask_b32_e64 v164, v164, 5, s[8:9]
	v_cndmask_b32_e64 v45, v45, v161, s[28:29]
	v_cndmask_b32_e64 v165, v165, 5, s[28:29]
	v_add_u32_sdwa v158, v170, v158 dst_sel:DWORD dst_unused:UNUSED_PAD src0_sel:WORD_1 src1_sel:DWORD
	v_add_u32_sdwa v159, v178, v159 dst_sel:DWORD dst_unused:UNUSED_PAD src0_sel:WORD_1 src1_sel:DWORD
	v_add_u32_sdwa v160, v186, v160 dst_sel:DWORD dst_unused:UNUSED_PAD src0_sel:WORD_1 src1_sel:DWORD
	v_add_u32_sdwa v161, v228, v161 dst_sel:DWORD dst_unused:UNUSED_PAD src0_sel:WORD_1 src1_sel:DWORD
	v_cmp_lt_u32_e64 s[4:5], v158, v238
	v_cmp_lt_u32_e64 s[6:7], v159, v239
	v_cmp_lt_u32_e64 s[8:9], v160, v240
	v_cmp_lt_u32_e64 s[28:29], v161, v241
	v_cndmask_b32_e64 v42, v42, v158, s[4:5]
	v_cndmask_b32_e64 v162, v162, 4, s[4:5]
	v_cndmask_b32_e64 v43, v43, v159, s[6:7]
	v_cndmask_b32_e64 v163, v163, 4, s[6:7]
	v_cndmask_b32_e64 v44, v44, v160, s[8:9]
	v_cndmask_b32_e64 v164, v164, 4, s[8:9]
	v_cndmask_b32_e64 v45, v45, v161, s[28:29]
	v_cndmask_b32_e64 v165, v165, 4, s[28:29]
	v_add_u32_sdwa v158, v170, v158 dst_sel:DWORD dst_unused:UNUSED_PAD src0_sel:WORD_0 src1_sel:DWORD
	v_add_u32_sdwa v159, v178, v159 dst_sel:DWORD dst_unused:UNUSED_PAD src0_sel:WORD_0 src1_sel:DWORD
	v_add_u32_sdwa v160, v186, v160 dst_sel:DWORD dst_unused:UNUSED_PAD src0_sel:WORD_0 src1_sel:DWORD
	v_add_u32_sdwa v161, v228, v161 dst_sel:DWORD dst_unused:UNUSED_PAD src0_sel:WORD_0 src1_sel:DWORD
	v_cmp_lt_u32_e64 s[4:5], v158, v238
; DI void idx_scan(const u32* hq, int need, u32* outbin, u32* outneed, int q, int lane) {
;     ...
;   if ((int)above < need && need <= (int)incl) {
;     u32 cum = above;
;     ...
;       u32 cnt = (hq[bin >> 1] >> ((bin & 1) * 16)) & 0xffffu;
;       if ((int)(cum + cnt) >= need) { outbin[q] = (u32)bin; outneed[q] = (u32)need - cum; break; }
;       cum += cnt;
;     }
; DI void idx_job(const Params& p, int b, int qg, unsigned char* smem) {
;     ...
;   for (int qq = 0; qq < 4; ++qq) idx_scan(hist + (wave * 4 + qq) * 512, (int)needB[wave * 4 + qq], binB, needC, wave * 4 + qq, lane);
;   __syncthreads();
;   idx_pass<2>(kp, qf, wq, wave, ntile, lm, lg, tq, selall, binA[lm], (binA[lm] << 10) | binB[lm], hist, maskw, cand, ccnt);
	v_cmp_lt_u32_e64 s[6:7], v159, v239
	v_cmp_lt_u32_e64 s[8:9], v160, v240
	v_cmp_lt_u32_e64 s[28:29], v161, v241
	v_cndmask_b32_e64 v42, v42, v158, s[4:5]
	v_cndmask_b32_e64 v162, v162, 3, s[4:5]
	v_cndmask_b32_e64 v43, v43, v159, s[6:7]
	v_cndmask_b32_e64 v163, v163, 3, s[6:7]
	v_cndmask_b32_e64 v44, v44, v160, s[8:9]
	v_cndmask_b32_e64 v164, v164, 3, s[8:9]
	v_cndmask_b32_e64 v45, v45, v161, s[28:29]
	v_cndmask_b32_e64 v165, v165, 3, s[28:29]
	v_add_u32_sdwa v158, v169, v158 dst_sel:DWORD dst_unused:UNUSED_PAD src0_sel:WORD_1 src1_sel:DWORD
	v_add_u32_sdwa v159, v177, v159 dst_sel:DWORD dst_unused:UNUSED_PAD src0_sel:WORD_1 src1_sel:DWORD
	v_add_u32_sdwa v160, v185, v160 dst_sel:DWORD dst_unused:UNUSED_PAD src0_sel:WORD_1 src1_sel:DWORD
	v_add_u32_sdwa v161, v227, v161 dst_sel:DWORD dst_unused:UNUSED_PAD src0_sel:WORD_1 src1_sel:DWORD
	v_cmp_lt_u32_e64 s[4:5], v158, v238
	v_cmp_lt_u32_e64 s[6:7], v159, v239
	v_cmp_lt_u32_e64 s[8:9], v160, v240
	v_cmp_lt_u32_e64 s[28:29], v161, v241
	v_cndmask_b32_e64 v42, v42, v158, s[4:5]
	v_cndmask_b32_e64 v162, v162, 2, s[4:5]
	v_cndmask_b32_e64 v43, v43, v159, s[6:7]
	v_cndmask_b32_e64 v163, v163, 2, s[6:7]
	v_cndmask_b32_e64 v44, v44, v160, s[8:9]
	v_cndmask_b32_e64 v164, v164, 2, s[8:9]
	v_cndmask_b32_e64 v45, v45, v161, s[28:29]
	v_cndmask_b32_e64 v165, v165, 2, s[28:29]
	v_add_u32_sdwa v158, v169, v158 dst_sel:DWORD dst_unused:UNUSED_PAD src0_sel:WORD_0 src1_sel:DWORD
	v_add_u32_sdwa v159, v177, v159 dst_sel:DWORD dst_unused:UNUSED_PAD src0_sel:WORD_0 src1_sel:DWORD
	v_add_u32_sdwa v160, v185, v160 dst_sel:DWORD dst_unused:UNUSED_PAD src0_sel:WORD_0 src1_sel:DWORD
	v_add_u32_sdwa v161, v227, v161 dst_sel:DWORD dst_unused:UNUSED_PAD src0_sel:WORD_0 src1_sel:DWORD
	v_cmp_lt_u32_e64 s[4:5], v158, v238
	v_cmp_lt_u32_e64 s[6:7], v159, v239
	v_cmp_lt_u32_e64 s[8:9], v160, v240
	v_cmp_lt_u32_e64 s[28:29], v161, v241
	v_cndmask_b32_e64 v42, v42, v158, s[4:5]
	v_cndmask_b32_e64 v162, v162, 1, s[4:5]
	v_cndmask_b32_e64 v43, v43, v159, s[6:7]
	v_cndmask_b32_e64 v163, v163, 1, s[6:7]
	v_cndmask_b32_e64 v44, v44, v160, s[8:9]
	v_cndmask_b32_e64 v164, v164, 1, s[8:9]
	v_cndmask_b32_e64 v45, v45, v161, s[28:29]
	v_cndmask_b32_e64 v165, v165, 1, s[28:29]
	v_add_u32_sdwa v158, v168, v158 dst_sel:DWORD dst_unused:UNUSED_PAD src0_sel:WORD_1 src1_sel:DWORD
	v_add_u32_sdwa v159, v176, v159 dst_sel:DWORD dst_unused:UNUSED_PAD src0_sel:WORD_1 src1_sel:DWORD
	v_add_u32_sdwa v160, v184, v160 dst_sel:DWORD dst_unused:UNUSED_PAD src0_sel:WORD_1 src1_sel:DWORD
	v_add_u32_sdwa v161, v226, v161 dst_sel:DWORD dst_unused:UNUSED_PAD src0_sel:WORD_1 src1_sel:DWORD
	v_cmp_lt_u32_e64 s[4:5], v158, v238
	v_cmp_lt_u32_e64 s[6:7], v159, v239
	v_cmp_lt_u32_e64 s[8:9], v160, v240
	v_cmp_lt_u32_e64 s[28:29], v161, v241
	v_cndmask_b32_e64 v42, v42, v158, s[4:5]
	v_cndmask_b32_e64 v162, v162, 0, s[4:5]
	v_cndmask_b32_e64 v43, v43, v159, s[6:7]
	v_cndmask_b32_e64 v163, v163, 0, s[6:7]
	v_cndmask_b32_e64 v44, v44, v160, s[8:9]
	v_cndmask_b32_e64 v164, v164, 0, s[8:9]
	v_cndmask_b32_e64 v45, v45, v161, s[28:29]
	v_cndmask_b32_e64 v165, v165, 0, s[28:29]
	v_add_u32_sdwa v158, v168, v158 dst_sel:DWORD dst_unused:UNUSED_PAD src0_sel:WORD_0 src1_sel:DWORD
	v_add_u32_sdwa v159, v176, v159 dst_sel:DWORD dst_unused:UNUSED_PAD src0_sel:WORD_0 src1_sel:DWORD
	v_add_u32_sdwa v160, v184, v160 dst_sel:DWORD dst_unused:UNUSED_PAD src0_sel:WORD_0 src1_sel:DWORD
	v_add_u32_sdwa v161, v226, v161 dst_sel:DWORD dst_unused:UNUSED_PAD src0_sel:WORD_0 src1_sel:DWORD
	v_cmp_lt_u32_e64 s[4:5], v158, v238
	v_cmp_lt_u32_e64 s[6:7], v159, v239
	v_cmp_lt_u32_e64 s[8:9], v160, v240
	v_cmp_lt_u32_e64 s[28:29], v161, v241
	v_cndmask_b32_e64 v42, v42, v158, s[4:5]
	v_cndmask_b32_e64 v162, v162, -1, s[4:5]
	v_cndmask_b32_e64 v43, v43, v159, s[6:7]
	v_cndmask_b32_e64 v163, v163, -1, s[6:7]
	v_cndmask_b32_e64 v44, v44, v160, s[8:9]
	v_cndmask_b32_e64 v164, v164, -1, s[8:9]
	v_cndmask_b32_e64 v45, v45, v161, s[28:29]
	v_cndmask_b32_e64 v165, v165, -1, s[28:29]
	v_lshl_add_u32 v50, v48, 4, v162
	v_lshl_add_u32 v51, v48, 4, v163
	v_lshl_add_u32 v52, v48, 4, v164
	v_lshl_add_u32 v53, v48, 4, v165
	v_sub_u32_e32 v54, v238, v42
	v_sub_u32_e32 v55, v239, v43
	v_sub_u32_e32 v242, v240, v44
	v_sub_u32_e32 v243, v241, v45
	s_mov_b64 exec, s[40:41]
	ds_write2_b32 v47, v50, v54 offset0:112 offset1:128
	s_mov_b64 exec, s[42:43]
	ds_write2_b32 v47, v51, v55 offset0:113 offset1:129
	s_mov_b64 exec, s[44:45]
	ds_write2_b32 v47, v52, v242 offset0:114 offset1:130
	s_mov_b64 exec, s[46:47]
	ds_write2_b32 v47, v53, v243 offset0:115 offset1:131
	s_mov_b64 exec, -1
	s_waitcnt lgkmcnt(0)
	s_barrier
	s_cbranch_vccnz .Lidx2_pj
	global_load_dwordx4 v[42:45], v[92:93], off
	global_load_dwordx4 v[46:49], v[94:95], off

; template <int PASS, bool DIAG>
; DI void idx_tile(const bf16x8 kf, const bf16x8 (&qf)[8], const float (&wq)[8], int kt, int lm, int lg, int tq, bool selall, u32 bA, u32 pfx,
;                  u32* hist, u32* maskw, u32* cand, u32* ccnt) {
;     ...
;     } else {
;       const u32 pp = u >> 12;
;       if (valid && (selall || pp > pfx)) selbits |= 1u << r;
;       if (valid && !selall && pp == pfx) {
;         const u32 ix = atomicAdd(&ccnt[lm], 1u);
;         if (ix < 64u) { cand[(lm * 64 + ix) * 2] = u; cand[(lm * 64 + ix) * 2 + 1] = (u32)key; }
;       }
; template <int PASS>
; DI void idx_pass(const u16* kp, const bf16x8 (&qf)[8], const float (&wq)[8], int wave, int ntile, int lm, int lg, int tq, bool selall,
;                  u32 bA, u32 pfx, u32* hist, u32* maskw, u32* cand, u32* ccnt) {
;     ...
;   for (; kt + 4 < ntile - 1; kt += 8) {
;     const bf16x8 kc = ldk(kt + 8), kd = ldk(kt + 12);
;     idx_tile<PASS, false>(ka, qf, wq, kt, lm, lg, tq, selall, bA, pfx, hist, maskw, cand, ccnt);
;     idx_tile<PASS, false>(kb, qf, wq, kt + 4, lm, lg, tq, selall, bA, pfx, hist, maskw, cand, ccnt);
;     ka = kc; kb = kd;
.Lidx2_loop:
	s_waitcnt vmcnt(2)
	v_mov_b64_e32 v[82:83], v[110:111]
	v_mov_b64_e32 v[84:85], v[112:113]
	v_mov_b64_e32 v[46:47], v[114:115]
	v_mov_b64_e32 v[48:49], v[116:117]
	global_load_dwordx4 v[110:113], v134, s[90:91]
	global_load_dwordx4 v[114:117], v134, s[92:93]
	v_add_u32_e32 v134, 0x2000, v134
	v_add_u32_e32 v93, v98, v102
	v_ashrrev_i32_e32 v181, 31, v82
	v_bitop3_b32 v168, v181, v82, s39 bitop3:0x36
	v_lshrrev_b32_e32 v176, 12, v168
	v_ashrrev_i32_e32 v181, 31, v83
	v_bitop3_b32 v170, v181, v83, s39 bitop3:0x36
	v_lshrrev_b32_e32 v177, 12, v170
	v_ashrrev_i32_e32 v181, 31, v84
	v_bitop3_b32 v172, v181, v84, s39 bitop3:0x36
	v_lshrrev_b32_e32 v178, 12, v172
	v_ashrrev_i32_e32 v181, 31, v85
	v_bitop3_b32 v174, v181, v85, s39 bitop3:0x36
	v_lshrrev_b32_e32 v179, 12, v174
	v_cmp_eq_u32_e64 s[8:9], v176, v99
	v_cmp_eq_u32_e64 s[28:29], v177, v99
	v_cmp_eq_u32_e64 s[94:95], v178, v99
	v_cmp_eq_u32_e32 vcc, v179, v99
	s_or_b64 s[8:9], s[8:9], s[28:29]
	s_or_b64 s[28:29], vcc, s[94:95]
	s_or_b64 s[8:9], s[8:9], s[28:29]
	s_and_b64 s[8:9], s[8:9], s[6:7]
	s_cbranch_scc0 .Lidx2_nc0
	v_cmp_eq_u32_e32 vcc, v176, v99
	s_and_b64 s[28:29], s[6:7], vcc
	s_and_saveexec_b64 s[8:9], s[28:29]
	s_cbranch_execz .Lidx2_c0_0
	ds_add_rtn_u32 v181, v136, v203 offset:49408
	s_waitcnt lgkmcnt(0)
	v_cmp_gt_u32_e32 vcc, 64, v181
	s_and_b64 exec, exec, vcc
	v_subrev_u32_e32 v169, 64, v93
	v_lshl_add_u32 v181, v181, 3, v100
	ds_write_b64 v181, v[168:169] offset:41216

; template <int PASS, bool DIAG>
; DI void idx_tile(const bf16x8 kf, const bf16x8 (&qf)[8], const float (&wq)[8], int kt, int lm, int lg, int tq, bool selall, u32 bA, u32 pfx,
;                  u32* hist, u32* maskw, u32* cand, u32* ccnt) {
;     ...
;     } else {
;       const u32 pp = u >> 12;
;       if (valid && (selall || pp > pfx)) selbits |= 1u << r;
;       if (valid && !selall && pp == pfx) {
;         const u32 ix = atomicAdd(&ccnt[lm], 1u);
;         if (ix < 64u) { cand[(lm * 64 + ix) * 2] = u; cand[(lm * 64 + ix) * 2 + 1] = (u32)key; }
;       }
; template <int PASS>
; DI void idx_pass(const u16* kp, const bf16x8 (&qf)[8], const float (&wq)[8], int wave, int ntile, int lm, int lg, int tq, bool selall,
;                  u32 bA, u32 pfx, u32* hist, u32* maskw, u32* cand, u32* ccnt) {
;     ...
;   for (; kt + 4 < ntile - 1; kt += 8) {
;     const bf16x8 kc = ldk(kt + 8), kd = ldk(kt + 12);
;     idx_tile<PASS, false>(ka, qf, wq, kt, lm, lg, tq, selall, bA, pfx, hist, maskw, cand, ccnt);
;     idx_tile<PASS, false>(kb, qf, wq, kt + 4, lm, lg, tq, selall, bA, pfx, hist, maskw, cand, ccnt);
;     ka = kc; kb = kd;
.Lidx2_o1:
	s_or_b64 exec, exec, s[8:9]
	v_add_u32_e32 v102, 0x80, v102
	v_add_u32_e32 v109, 8, v109
	s_add_i32 s88, s88, 8
	s_add_i32 s4, s88, 4
	s_cmp_ge_i32 s4, s89
	s_cbranch_scc1 .Lidx2_done
	s_waitcnt vmcnt(2)
	v_mov_b64_e32 v[82:83], v[118:119]
	v_mov_b64_e32 v[84:85], v[120:121]
	v_mov_b64_e32 v[46:47], v[122:123]
	v_mov_b64_e32 v[48:49], v[124:125]
	global_load_dwordx4 v[118:121], v134, s[90:91]
	global_load_dwordx4 v[122:125], v134, s[92:93]
	v_add_u32_e32 v134, 0x2000, v134
	v_add_u32_e32 v93, v98, v102
	v_ashrrev_i32_e32 v181, 31, v82
	v_bitop3_b32 v168, v181, v82, s39 bitop3:0x36
	v_lshrrev_b32_e32 v176, 12, v168
	v_ashrrev_i32_e32 v181, 31, v83
	v_bitop3_b32 v170, v181, v83, s39 bitop3:0x36
	v_lshrrev_b32_e32 v177, 12, v170
	v_ashrrev_i32_e32 v181, 31, v84
	v_bitop3_b32 v172, v181, v84, s39 bitop3:0x36
	v_lshrrev_b32_e32 v178, 12, v172
	v_ashrrev_i32_e32 v181, 31, v85
	v_bitop3_b32 v174, v181, v85, s39 bitop3:0x36
	v_lshrrev_b32_e32 v179, 12, v174
	v_cmp_eq_u32_e64 s[8:9], v176, v99
	v_cmp_eq_u32_e64 s[28:29], v177, v99
	v_cmp_eq_u32_e64 s[94:95], v178, v99
	v_cmp_eq_u32_e32 vcc, v179, v99
	s_or_b64 s[8:9], s[8:9], s[28:29]
	s_or_b64 s[28:29], vcc, s[94:95]
	s_or_b64 s[8:9], s[8:9], s[28:29]
	s_and_b64 s[8:9], s[8:9], s[6:7]
	s_cbranch_scc0 .Lidx2_nc2
	v_cmp_eq_u32_e32 vcc, v176, v99
	s_and_b64 s[28:29], s[6:7], vcc
	s_and_saveexec_b64 s[8:9], s[28:29]
	s_cbranch_execz .Lidx2_c2_0
	ds_add_rtn_u32 v181, v136, v203 offset:49408
	s_waitcnt lgkmcnt(0)
	v_cmp_gt_u32_e32 vcc, 64, v181
	s_and_b64 exec, exec, vcc
	v_subrev_u32_e32 v169, 64, v93
	v_lshl_add_u32 v181, v181, 3, v100
	ds_write_b64 v181, v[168:169] offset:41216

; template <int PASS>
; DI void idx_pass(const u16* kp, const bf16x8 (&qf)[8], const float (&wq)[8], int wave, int ntile, int lm, int lg, int tq, bool selall,
;                  u32 bA, u32 pfx, u32* hist, u32* maskw, u32* cand, u32* ccnt) {
;     ...
;   }
;   if (kt < ntile - 1) { idx_tile<PASS, false>(ka, qf, wq, kt, lm, lg, tq, selall, bA, pfx, hist, maskw, cand, ccnt); kt += 4; ka = kb; }
;   if (kt == ntile - 1) idx_tile<PASS, true>(ka, qf, wq, kt, lm, lg, tq, selall, bA, pfx, hist, maskw, cand, ccnt);
.Lidx2_done:
	s_waitcnt vmcnt(0)
	v_mov_b64_e32 v[42:43], v[126:127]
	v_mov_b64_e32 v[44:45], v[128:129]
	v_mov_b64_e32 v[46:47], v[130:131]
	v_mov_b64_e32 v[48:49], v[132:133]
	v_add_u32_e32 v0, 4, v109
	v_mov_b32_e32 v103, v109
